# attention loop: K/Kpe LDS staging writes moved ahead of the first tile barrier
# speedup vs baseline: 1.0156x; 1.0156x over previous
; __device__ __forceinline__ void finishSM(f32x16& p0, f32x16& p1, float alpha, float& l_reg, bf16x8& pa0, bf16x8& pa1, bf16x8& pa2, bf16x8& pa3) {
;   for (int r = 0; r < 16; ++r) p1[r] = __builtin_amdgcn_exp2f(p1[r]);
;   float ps = 0; for (int r = 0; r < 16; ++r) ps += p0[r]; for (int r = 0; r < 16; ++r) ps += p1[r];
;   { auto rr = __builtin_amdgcn_permlane32_swap(__float_as_uint(ps), __float_as_uint(ps), false, false);
;     ps = __uint_as_float(rr[0]) + __uint_as_float(rr[1]); }
;   l_reg = l_reg * alpha + ps;
;     ...
;   PK4(p0, 0, pa0); PK4(p0, 8, pa1); PK4(p1, 0, pa2); PK4(p1, 8, pa3);
;     ...
; }
; __device__ __forceinline__ void qkt(f32x16& p0, f32x16& p1, const char* Kn, const char* Kp, const bf16x8* qr, int r32, int hi) {
;   p0 = f32x16{}; p1 = f32x16{};
; #pragma unroll
;   for (int d0 = 0; d0 < 8; ++d0) { int cb = (d0 * 16 + hi * 8) * 2;
;     bf16x8 b0 = *reinterpret_cast<const bf16x8*>(Kn + KSWZ(r32, cb));
;     bf16x8 b1 = *reinterpret_cast<const bf16x8*>(Kn + KSWZ(32 + r32, cb));
;     p0 = __builtin_amdgcn_mfma_f32_32x32x16_bf16(b0, qr[d0], p0, 0, 0, 0);
;     p1 = __builtin_amdgcn_mfma_f32_32x32x16_bf16(b1, qr[d0], p1, 0, 0, 0); }
; #pragma unroll
;   for (int d1 = 0; d1 < 4; ++d1) { int cb = (d1 * 16 + hi * 8) * 2;
;     bf16x8 b0 = *reinterpret_cast<const bf16x8*>(Kp + KPSWZ(r32, cb));
;     bf16x8 b1 = *reinterpret_cast<const bf16x8*>(Kp + KPSWZ(32 + r32, cb));
;     p0 = __builtin_amdgcn_mfma_f32_32x32x16_bf16(b0, qr[8 + d1], p0, 0, 0, 0);
;     p1 = __builtin_amdgcn_mfma_f32_32x32x16_bf16(b1, qr[8 + d1], p1, 0, 0, 0); }
; }
.LBB0_1453:
	s_add_i32 s11, s11, 2
	ds_read_b128 v[64:67], v205 offset:49152
	ds_read_b128 v[68:71], v205 offset:57344
	ds_read_b128 v[226:229], v206 offset:49152
	ds_read_b128 v[238:241], v206 offset:57344
	s_add_i32 s8, 0, 0x12000
	v_add_u32_e32 v225, s8, v213
	s_waitcnt lgkmcnt(3)
	v_mfma_f32_32x32x16_bf16 v[80:95], v[64:67], v[136:139], 0
	v_add_f32_e32 v164, 0, v234
	v_add_f32_e32 v164, v236, v164
	v_add_f32_e32 v164, v165, v164
	v_add_f32_e32 v164, v235, v164
	v_add_f32_e32 v164, v166, v164
	v_add_f32_e32 v164, v233, v164
	v_add_f32_e32 v164, v167, v164
	s_waitcnt lgkmcnt(2)
	v_mfma_f32_32x32x16_bf16 v[64:79], v[68:71], v[136:139], 0
	v_add_f32_e32 v164, v232, v164
	v_add_f32_e32 v164, v168, v164
	v_add_f32_e32 v164, v171, v164
	v_add_f32_e32 v164, v169, v164
	v_add_f32_e32 v164, v170, v164
	v_exp_f32_e32 v156, v156
	v_add_f32_e32 v164, v161, v164
	s_waitcnt lgkmcnt(1)
	v_mfma_f32_32x32x16_bf16 v[80:95], v[226:229], v[132:135], v[80:95]
	v_exp_f32_e32 v157, v157
	v_add_f32_e32 v164, v163, v164
	v_exp_f32_e32 v154, v154
	v_add_f32_e32 v164, v160, v164
	v_exp_f32_e32 v155, v155
	v_add_f32_e32 v164, v162, v164
	v_exp_f32_e32 v148, v148
	s_waitcnt lgkmcnt(0)
	v_mfma_f32_32x32x16_bf16 v[64:79], v[238:241], v[132:135], v[64:79]
	ds_read_b128 v[226:229], v208 offset:49152
	ds_read_b128 v[238:241], v208 offset:57344
	v_add_f32_e32 v164, v156, v164
	v_exp_f32_e32 v149, v149
	v_add_f32_e32 v164, v157, v164
	v_exp_f32_e32 v146, v146
	v_add_f32_e32 v164, v154, v164
	v_exp_f32_e32 v147, v147
	s_waitcnt lgkmcnt(1)
	v_mfma_f32_32x32x16_bf16 v[80:95], v[226:229], v[128:131], v[80:95]
	v_add_f32_e32 v164, v155, v164
	v_exp_f32_e32 v144, v144
	v_add_f32_e32 v164, v148, v164
	v_exp_f32_e32 v145, v145
	v_add_f32_e32 v164, v149, v164
	v_exp_f32_e32 v158, v158
	v_add_f32_e32 v164, v146, v164
	s_waitcnt lgkmcnt(0)
	v_mfma_f32_32x32x16_bf16 v[64:79], v[238:241], v[128:131], v[64:79]
	ds_read_b128 v[226:229], v209 offset:49152
	ds_read_b128 v[238:241], v209 offset:57344
	v_exp_f32_e32 v159, v159
	v_add_f32_e32 v164, v147, v164
	v_exp_f32_e32 v152, v152
	v_add_f32_e32 v164, v144, v164
	v_exp_f32_e32 v153, v153
	v_add_f32_e32 v164, v145, v164
	s_waitcnt lgkmcnt(1)
	v_mfma_f32_32x32x16_bf16 v[80:95], v[226:229], v[124:127], v[80:95]
	v_exp_f32_e32 v150, v150
	v_add_f32_e32 v164, v158, v164
	v_exp_f32_e32 v151, v151
	v_add_f32_e32 v164, v159, v164
	v_add_f32_e32 v164, v152, v164
	v_add_f32_e32 v164, v153, v164
	v_add_f32_e32 v164, v150, v164
	s_waitcnt lgkmcnt(0)
	v_mfma_f32_32x32x16_bf16 v[64:79], v[238:241], v[124:127], v[64:79]
	ds_read_b128 v[226:229], v210 offset:49152
	ds_read_b128 v[238:241], v210 offset:57344
	s_waitcnt lgkmcnt(1)
	v_mfma_f32_32x32x16_bf16 v[80:95], v[226:229], v[120:123], v[80:95]
	s_waitcnt lgkmcnt(0)
	v_mfma_f32_32x32x16_bf16 v[64:79], v[238:241], v[120:123], v[64:79]
	ds_read_b128 v[226:229], v212 offset:49152
	ds_read_b128 v[238:241], v212 offset:57344
	s_waitcnt lgkmcnt(1)
	v_mfma_f32_32x32x16_bf16 v[80:95], v[226:229], v[140:143], v[80:95]
	s_waitcnt lgkmcnt(0)
	v_mfma_f32_32x32x16_bf16 v[64:79], v[238:241], v[140:143], v[64:79]
	ds_read_b128 v[226:229], v211 offset:49152
	ds_read_b128 v[238:241], v211 offset:57344
	s_waitcnt lgkmcnt(1)
	v_mfma_f32_32x32x16_bf16 v[80:95], v[226:229], v[116:119], v[80:95]
	s_waitcnt lgkmcnt(0)
	v_mfma_f32_32x32x16_bf16 v[64:79], v[238:241], v[116:119], v[64:79]
	ds_read_b128 v[226:229], v207 offset:49152
	ds_read_b128 v[238:241], v207 offset:57344
	s_waitcnt lgkmcnt(1)
	v_mfma_f32_32x32x16_bf16 v[80:95], v[226:229], v[112:115], v[80:95]
	s_waitcnt lgkmcnt(0)
	v_mfma_f32_32x32x16_bf16 v[64:79], v[238:241], v[112:115], v[64:79]
	ds_read_b128 v[226:229], v225
	ds_read_b128 v[238:241], v225 offset:4096
	s_waitcnt lgkmcnt(1)
	v_mfma_f32_32x32x16_bf16 v[80:95], v[226:229], v[108:111], v[80:95]
	v_add_u32_e32 v227, s8, v215
	v_add_u32_e32 v226, s8, v219
	s_waitcnt lgkmcnt(0)
	v_mfma_f32_32x32x16_bf16 v[64:79], v[238:241], v[108:111], v[64:79]
	ds_read_b128 v[228:231], v227
	ds_read_b128 v[238:241], v227 offset:4096
	s_waitcnt lgkmcnt(1)
	v_mfma_f32_32x32x16_bf16 v[80:95], v[228:231], v[104:107], v[80:95]
	v_add_u32_e32 v228, s8, v217
	v_add_f32_e32 v229, v151, v164
	v_mov_b32_e32 v230, v229
	s_nop 1
	v_permlane32_swap_b32_e32 v229, v230
	s_waitcnt lgkmcnt(0)
	v_mfma_f32_32x32x16_bf16 v[64:79], v[238:241], v[104:107], v[64:79]
	ds_read_b128 v[238:241], v228
	ds_read_b128 v[242:245], v228 offset:4096
	s_waitcnt lgkmcnt(1)
	v_mfma_f32_32x32x16_bf16 v[80:95], v[238:241], v[100:103], v[80:95]
	s_waitcnt lgkmcnt(0)
	v_mfma_f32_32x32x16_bf16 v[64:79], v[242:245], v[100:103], v[64:79]
	ds_read_b128 v[238:241], v226
	ds_read_b128 v[242:245], v226 offset:4096
	v_cvt_pk_bf16_f32 v164, v234, v236
	v_cvt_pk_bf16_f32 v165, v165, v235
	v_cvt_pk_bf16_f32 v166, v166, v233
	v_cvt_pk_bf16_f32 v167, v167, v232
	v_cvt_pk_bf16_f32 v168, v168, v171
	v_cvt_pk_bf16_f32 v169, v169, v170
	s_waitcnt lgkmcnt(1)
	v_mfma_f32_32x32x16_bf16 v[80:95], v[238:241], v[96:99], v[80:95]
	v_permlane32_swap_b32_e32 v164, v166
	v_cvt_pk_bf16_f32 v170, v161, v163
	v_cvt_pk_bf16_f32 v171, v160, v162
	v_cvt_pk_bf16_f32 v232, v156, v157
	v_cvt_pk_bf16_f32 v233, v154, v155
	v_cvt_pk_bf16_f32 v234, v148, v149
	s_waitcnt lgkmcnt(0)
; __device__ __forceinline__ void finishSM(f32x16& p0, f32x16& p1, float alpha, float& l_reg, bf16x8& pa0, bf16x8& pa1, bf16x8& pa2, bf16x8& pa3) {
;   for (int r = 0; r < 16; ++r) p1[r] = __builtin_amdgcn_exp2f(p1[r]);
;   float ps = 0; for (int r = 0; r < 16; ++r) ps += p0[r]; for (int r = 0; r < 16; ++r) ps += p1[r];
;   { auto rr = __builtin_amdgcn_permlane32_swap(__float_as_uint(ps), __float_as_uint(ps), false, false);
;     ps = __uint_as_float(rr[0]) + __uint_as_float(rr[1]); }
;   l_reg = l_reg * alpha + ps;
;     ...
;   PK4(p0, 0, pa0); PK4(p0, 8, pa1); PK4(p1, 0, pa2); PK4(p1, 8, pa3);
;     ...
; }
; __device__ __forceinline__ void qkt(f32x16& p0, f32x16& p1, const char* Kn, const char* Kp, const bf16x8* qr, int r32, int hi) {
;   p0 = f32x16{}; p1 = f32x16{};
; #pragma unroll
;   for (int d0 = 0; d0 < 8; ++d0) { int cb = (d0 * 16 + hi * 8) * 2;
;     bf16x8 b0 = *reinterpret_cast<const bf16x8*>(Kn + KSWZ(r32, cb));
;     bf16x8 b1 = *reinterpret_cast<const bf16x8*>(Kn + KSWZ(32 + r32, cb));
;     p0 = __builtin_amdgcn_mfma_f32_32x32x16_bf16(b0, qr[d0], p0, 0, 0, 0);
;     p1 = __builtin_amdgcn_mfma_f32_32x32x16_bf16(b1, qr[d0], p1, 0, 0, 0); }
; #pragma unroll
;   for (int d1 = 0; d1 < 4; ++d1) { int cb = (d1 * 16 + hi * 8) * 2;
;     bf16x8 b0 = *reinterpret_cast<const bf16x8*>(Kp + KPSWZ(r32, cb));
;     bf16x8 b1 = *reinterpret_cast<const bf16x8*>(Kp + KPSWZ(32 + r32, cb));
;     p0 = __builtin_amdgcn_mfma_f32_32x32x16_bf16(b0, qr[8 + d1], p0, 0, 0, 0);
;     p1 = __builtin_amdgcn_mfma_f32_32x32x16_bf16(b1, qr[8 + d1], p1, 0, 0, 0); }
; }
; __device__ __forceinline__ int v_st(int k, int c) { const int kk = (k & ~0xC) | ((k & 4) << 1) | ((k & 8) >> 1); return ((kk >> 3) * 4 + (c >> 5)) * 512 + ((kk & 7) * 32 + (c & 31)) * 2; }
; __device__ __forceinline__ int v_rd_base(int lane) { return ((lane & 3) << 3) | (((lane >> 2) & 3) << 6) | (((lane >> 4) & 1) << 5) | (((lane >> 5) & 1) << 8); }
; template <int OFF> __device__ __forceinline__ s16x4 tr_read(int vb) {
;   s16x4 r; asm volatile("ds_read_b64_tr_b16 %0, %1 offset:%2" : "=&v"(r) : "v"(vb), "i"(OFF) : "memory"); return r;
; }
; template <int D0> __device__ __forceinline__ void pv_one(f32x16& od, int vb, bf16x8 pa0, bf16x8 pa1, bf16x8 pa2, bf16x8 pa3) {
	v_mfma_f32_32x32x16_bf16 v[64:79], v[242:245], v[96:99], v[64:79]
	v_cvt_pk_bf16_f32 v235, v146, v147
	v_cvt_pk_bf16_f32 v236, v144, v145
	v_cvt_pk_bf16_f32 v237, v158, v159
	v_cvt_pk_bf16_f32 v238, v152, v153
	v_cvt_pk_bf16_f32 v239, v150, v151
	v_permlane32_swap_b32_e32 v165, v167
	v_permlane32_swap_b32_e32 v168, v170
	v_permlane32_swap_b32_e32 v169, v171
	v_permlane32_swap_b32_e32 v232, v234
	v_permlane32_swap_b32_e32 v233, v235
	v_permlane32_swap_b32_e32 v236, v238
	v_permlane32_swap_b32_e32 v237, v239
	s_sub_i32 s8, s34, 64
	s_cmp_lt_u32 s11, 3
	s_cselect_b32 s8, s31, s8
	v_add_u32_e32 v144, s8, v198
	v_ashrrev_i32_e32 v145, 31, v144
	v_lshlrev_b64 v[144:145], 12, v[144:145]
	v_lshl_add_u64 v[148:149], v[180:181], 0, v[144:145]
	v_add_u32_e32 v144, s8, v200
	v_ashrrev_i32_e32 v145, 31, v144
	v_lshlrev_b64 v[144:145], 12, v[144:145]
	v_lshl_add_u64 v[152:153], v[180:181], 0, v[144:145]
	v_add_u32_e32 v160, s8, v199
	global_load_dwordx4 v[144:147], v[148:149], off offset:256
	s_nop 0
	global_load_dwordx4 v[148:151], v[148:149], off
	s_nop 0
	global_load_dwordx4 v[156:159], v[152:153], off offset:256
	s_nop 0
	global_load_dwordx4 v[152:155], v[152:153], off
	v_ashrrev_i32_e32 v161, 31, v160
	v_lshlrev_b64 v[160:161], 10, v[160:161]
	v_lshl_add_u64 v[160:161], v[182:183], 0, v[160:161]
	global_load_dwordx4 v[160:163], v[160:161], off
	ds_read_b64_tr_b16 v[240:241], v197 offset:0
	ds_read_b64_tr_b16 v[242:243], v197 offset:0x800
	ds_read_b64_tr_b16 v[244:245], v197 offset:0x1000
	ds_read_b64_tr_b16 v[246:247], v197 offset:0x1800
	ds_read_b64_tr_b16 v[248:249], v197 offset:0x2000
	ds_read_b64_tr_b16 v[250:251], v197 offset:0x2800
	ds_read_b64_tr_b16 v[192:193], v197 offset:0x3000
	ds_read_b64_tr_b16 v[194:195], v197 offset:0x3800
	s_waitcnt lgkmcnt(0)
	s_nop 0
	v_mfma_f32_32x32x16_bf16 v[0:15], v[164:167], v[240:243], v[0:15]
	v_mfma_f32_32x32x16_bf16 v[0:15], v[168:171], v[244:247], v[0:15]
	v_mfma_f32_32x32x16_bf16 v[0:15], v[232:235], v[248:251], v[0:15]
	v_mfma_f32_32x32x16_bf16 v[0:15], v[236:239], v[192:195], v[0:15]
	ds_read_b64_tr_b16 v[192:193], v197 offset:0x200
	ds_read_b64_tr_b16 v[194:195], v197 offset:0xa00
	ds_read_b64_tr_b16 v[240:241], v197 offset:0x1200
	ds_read_b64_tr_b16 v[242:243], v197 offset:0x1a00
	ds_read_b64_tr_b16 v[244:245], v197 offset:0x2200
	ds_read_b64_tr_b16 v[246:247], v197 offset:0x2a00
	ds_read_b64_tr_b16 v[248:249], v197 offset:0x3200
	ds_read_b64_tr_b16 v[250:251], v197 offset:0x3a00
	s_waitcnt lgkmcnt(0)
	s_nop 0
	v_mfma_f32_32x32x16_bf16 v[48:63], v[164:167], v[192:195], v[48:63]
	ds_read_b64_tr_b16 v[192:193], v197 offset:0x400
	ds_read_b64_tr_b16 v[194:195], v197 offset:0xc00
	v_mfma_f32_32x32x16_bf16 v[48:63], v[168:171], v[240:243], v[48:63]
	ds_read_b64_tr_b16 v[240:241], v197 offset:0x1400
	ds_read_b64_tr_b16 v[242:243], v197 offset:0x1c00
	v_mfma_f32_32x32x16_bf16 v[48:63], v[232:235], v[244:247], v[48:63]
	ds_read_b64_tr_b16 v[244:245], v197 offset:0x2400
	ds_read_b64_tr_b16 v[246:247], v197 offset:0x2c00
	v_mfma_f32_32x32x16_bf16 v[48:63], v[236:239], v[248:251], v[48:63]
	ds_read_b64_tr_b16 v[248:249], v197 offset:0x3400
	ds_read_b64_tr_b16 v[250:251], v197 offset:0x3c00
	s_waitcnt lgkmcnt(0)
	v_mfma_f32_32x32x16_bf16 v[32:47], v[164:167], v[192:195], v[32:47]
	ds_read_b64_tr_b16 v[192:193], v197 offset:0x600
	ds_read_b64_tr_b16 v[194:195], v197 offset:0xe00
	v_mfma_f32_32x32x16_bf16 v[32:47], v[168:171], v[240:243], v[32:47]
	ds_read_b64_tr_b16 v[240:241], v197 offset:0x1600
	ds_read_b64_tr_b16 v[242:243], v197 offset:0x1e00
	v_mfma_f32_32x32x16_bf16 v[32:47], v[232:235], v[244:247], v[32:47]
	ds_read_b64_tr_b16 v[244:245], v197 offset:0x2600
	ds_read_b64_tr_b16 v[246:247], v197 offset:0x2e00
	v_mfma_f32_32x32x16_bf16 v[32:47], v[236:239], v[248:251], v[32:47]
	ds_read_b64_tr_b16 v[248:249], v197 offset:0x3600
	ds_read_b64_tr_b16 v[250:251], v197 offset:0x3e00
	s_waitcnt lgkmcnt(0)
	v_mfma_f32_32x32x16_bf16 v[16:31], v[164:167], v[192:195], v[16:31]
	v_max_f32_e32 v164, v81, v81
	v_max_f32_e32 v165, v80, v80
	v_max_f32_e32 v164, v165, v164
	v_max3_f32 v164, v164, v82, v83
	v_max3_f32 v164, v164, v84, v85
	v_max3_f32 v164, v164, v86, v87
	v_max3_f32 v164, v164, v88, v89
	v_max3_f32 v164, v164, v90, v91
	v_max3_f32 v164, v164, v92, v93
	v_mfma_f32_32x32x16_bf16 v[16:31], v[168:171], v[240:243], v[16:31]
	v_max3_f32 v164, v164, v94, v95
	v_max3_f32 v164, v164, v64, v65
	v_max3_f32 v164, v164, v66, v67
	v_max3_f32 v164, v164, v68, v69
	v_max3_f32 v164, v164, v70, v71
	v_max3_f32 v164, v164, v72, v73
	v_max3_f32 v164, v164, v74, v75
	v_max3_f32 v164, v164, v76, v77
	v_mfma_f32_32x32x16_bf16 v[16:31], v[232:235], v[244:247], v[16:31]
	v_max3_f32 v164, v164, v78, v79
	v_mov_b32_e32 v165, v164
	s_nop 1
	v_permlane32_swap_b32_e32 v164, v165
	v_max_f32_e32 v165, v165, v165
	v_max_f32_e32 v164, v164, v164
	v_max_f32_e32 v164, v164, v165
	v_sub_f32_e32 v165, v164, v224
	v_cmp_ge_f32_e32 vcc, s33, v165
	v_max_f32_e32 v165, v224, v224
	v_max_f32_e32 v164, v165, v164
	v_mfma_f32_32x32x16_bf16 v[16:31], v[236:239], v[248:251], v[16:31]
	v_sub_f32_e32 v165, v224, v164
	v_mul_f32_e32 v165, 0x3dd53b94, v165
	v_exp_f32_e32 v165, v165
	s_cmp_eq_u64 vcc, exec
	s_cselect_b64 s[8:9], -1, 0
	s_waitcnt vmcnt(0)
	ds_write_b128 v203, v[148:151] offset:32768
	ds_write_b128 v204, v[152:155] offset:32768
	v_add_u32_e32 v240, 0x10000, v222
	ds_write_b128 v240, v[160:163]
	s_barrier
	s_waitcnt vmcnt(0)
	v_cndmask_b32_e64 v231, v165, 1.0, s[8:9]
	ds_write_b128 v201, v[144:147]
	ds_write_b128 v202, v[156:159]
	v_cmp_gt_f32_e32 vcc, 1.0, v231
	s_cbranch_vccz .LBB0_1457
; __device__ __forceinline__ void partialSM(f32x16& p0, f32x16& p1, float& m_reg, float& mn, float& alpha) {
;     ...
;   float mnC = -mn * C;
;   for (int r = 0; r < 16; ++r) p0[r] = fmaf(p0[r], C, mnC); for (int r = 0; r < 16; ++r) p1[r] = fmaf(p1[r], C, mnC);
;   for (int r = 0; r < 16; ++r) p0[r] = __builtin_amdgcn_exp2f(p0[r]);
; }
; __device__ __forceinline__ void finishSM(f32x16& p0, f32x16& p1, float alpha, float& l_reg, bf16x8& pa0, bf16x8& pa1, bf16x8& pa2, bf16x8& pa3) {
;   for (int r = 0; r < 16; ++r) p1[r] = __builtin_amdgcn_exp2f(p1[r]);
;   float ps = 0; for (int r = 0; r < 16; ++r) ps += p0[r]; for (int r = 0; r < 16; ++r) ps += p1[r];
;   { auto rr = __builtin_amdgcn_permlane32_swap(__float_as_uint(ps), __float_as_uint(ps), false, false);
;     ps = __uint_as_float(rr[0]) + __uint_as_float(rr[1]); }
;   l_reg = l_reg * alpha + ps;
;     ...
;   PK4(p0, 0, pa0); PK4(p0, 8, pa1); PK4(p1, 0, pa2); PK4(p1, 8, pa3);
;     ...
; }
; __device__ __forceinline__ void qkt(f32x16& p0, f32x16& p1, const char* Kn, const char* Kp, const bf16x8* qr, int r32, int hi) {
;   p0 = f32x16{}; p1 = f32x16{};
; #pragma unroll
;   for (int d0 = 0; d0 < 8; ++d0) { int cb = (d0 * 16 + hi * 8) * 2;
;     bf16x8 b0 = *reinterpret_cast<const bf16x8*>(Kn + KSWZ(r32, cb));
;     bf16x8 b1 = *reinterpret_cast<const bf16x8*>(Kn + KSWZ(32 + r32, cb));
;     p0 = __builtin_amdgcn_mfma_f32_32x32x16_bf16(b0, qr[d0], p0, 0, 0, 0);
;     p1 = __builtin_amdgcn_mfma_f32_32x32x16_bf16(b1, qr[d0], p1, 0, 0, 0); }
; #pragma unroll
;   for (int d1 = 0; d1 < 4; ++d1) { int cb = (d1 * 16 + hi * 8) * 2;
;     bf16x8 b0 = *reinterpret_cast<const bf16x8*>(Kp + KPSWZ(r32, cb));
;     bf16x8 b1 = *reinterpret_cast<const bf16x8*>(Kp + KPSWZ(32 + r32, cb));
;     p0 = __builtin_amdgcn_mfma_f32_32x32x16_bf16(b0, qr[8 + d1], p0, 0, 0, 0);
;     p1 = __builtin_amdgcn_mfma_f32_32x32x16_bf16(b1, qr[8 + d1], p1, 0, 0, 0); }
; }
; __device__ __forceinline__ void attn_unit(const bf16_t* __restrict__ Qb, const bf16_t* __restrict__ KV, const bf16_t* __restrict__ KP, bf16_t* __restrict__ Ob, ...
;     ...
;   f32x16 pA0, pA1, pB0, pB1; float mnA, mnB, alA, alB; bf16x8 pa0, pa1, pa2, pa3;
;   SLOAD(0); SWAIT(); SWRITE(0); __syncthreads();
;   qkt(pA0, pA1, KN_lds, KP_lds, qr, r32, hi); partialSM(pA0, pA1, m_reg, mnA, alA);
;   SLOAD(1);
;   SWAIT(); SWRITE(1); __syncthreads();
;   for (int j = 1; j + 1 < NT; j += 2) {
	s_and_saveexec_b64 s[24:25], s[6:7]
	ds_write_b32 v186, v231 offset:128
	s_or_b64 exec, exec, s[24:25]
	s_waitcnt lgkmcnt(0)
	v_add_u32_e32 v156, v179, v172
	ds_read_b128 v[144:147], v156 offset:224
	ds_read_b128 v[148:151], v156 offset:192
	ds_read_b128 v[152:155], v156 offset:160
	ds_read_b128 v[156:159], v156 offset:128
	s_waitcnt lgkmcnt(3)
	v_pk_mul_f32 v[12:13], v[12:13], v[144:145]
	s_waitcnt lgkmcnt(2)
	v_pk_mul_f32 v[8:9], v[8:9], v[148:149]
	s_waitcnt lgkmcnt(1)
	v_pk_mul_f32 v[4:5], v[4:5], v[152:153]
	v_pk_mul_f32 v[14:15], v[14:15], v[146:147]
	v_pk_mul_f32 v[10:11], v[10:11], v[150:151]
	v_pk_mul_f32 v[6:7], v[6:7], v[154:155]
	s_waitcnt lgkmcnt(0)
	v_pk_mul_f32 v[2:3], v[2:3], v[158:159]
	v_pk_mul_f32 v[0:1], v[0:1], v[156:157]
	v_pk_mul_f32 v[60:61], v[60:61], v[144:145]
	v_pk_mul_f32 v[56:57], v[56:57], v[148:149]
	v_pk_mul_f32 v[52:53], v[52:53], v[152:153]
	v_pk_mul_f32 v[62:63], v[62:63], v[146:147]
	v_pk_mul_f32 v[58:59], v[58:59], v[150:151]
	v_pk_mul_f32 v[54:55], v[54:55], v[154:155]
	v_pk_mul_f32 v[50:51], v[50:51], v[158:159]
	v_pk_mul_f32 v[48:49], v[48:49], v[156:157]
	v_pk_mul_f32 v[44:45], v[44:45], v[144:145]
	v_pk_mul_f32 v[40:41], v[40:41], v[148:149]
	v_pk_mul_f32 v[36:37], v[36:37], v[152:153]
	v_pk_mul_f32 v[46:47], v[46:47], v[146:147]
	v_pk_mul_f32 v[42:43], v[42:43], v[150:151]
	v_pk_mul_f32 v[38:39], v[38:39], v[154:155]
	v_pk_mul_f32 v[34:35], v[34:35], v[158:159]
	v_pk_mul_f32 v[32:33], v[32:33], v[156:157]
	v_pk_mul_f32 v[28:29], v[28:29], v[144:145]
	v_pk_mul_f32 v[24:25], v[24:25], v[148:149]
	v_pk_mul_f32 v[20:21], v[20:21], v[152:153]
	v_pk_mul_f32 v[30:31], v[30:31], v[146:147]
	v_pk_mul_f32 v[26:27], v[26:27], v[150:151]
	v_pk_mul_f32 v[22:23], v[22:23], v[154:155]
	v_pk_mul_f32 v[18:19], v[18:19], v[158:159]
	v_pk_mul_f32 v[16:17], v[16:17], v[156:157]
.LBB0_1457:
	v_cndmask_b32_e64 v224, v164, v224, s[8:9]
	v_mul_f32_e32 v160, 0xbdd53b94, v224
	v_fmamk_f32 v80, v80, 0x3dd53b94, v160
	v_fmamk_f32 v81, v81, 0x3dd53b94, v160
	v_fmamk_f32 v82, v82, 0x3dd53b94, v160
	v_fmamk_f32 v83, v83, 0x3dd53b94, v160
	v_fmamk_f32 v84, v84, 0x3dd53b94, v160
	v_fmamk_f32 v85, v85, 0x3dd53b94, v160
	v_fmamk_f32 v86, v86, 0x3dd53b94, v160
	v_fmamk_f32 v87, v87, 0x3dd53b94, v160
	v_fmamk_f32 v88, v88, 0x3dd53b94, v160
	v_fmamk_f32 v89, v89, 0x3dd53b94, v160
	v_fmamk_f32 v90, v90, 0x3dd53b94, v160
	v_fmamk_f32 v91, v91, 0x3dd53b94, v160
	v_fmamk_f32 v92, v92, 0x3dd53b94, v160
	v_fmamk_f32 v93, v93, 0x3dd53b94, v160
	v_fmamk_f32 v94, v94, 0x3dd53b94, v160
	v_fmamk_f32 v95, v95, 0x3dd53b94, v160
	v_fmamk_f32 v164, v71, 0x3dd53b94, v160
	v_fmamk_f32 v165, v72, 0x3dd53b94, v160
	v_fmamk_f32 v169, v64, 0x3dd53b94, v160
	v_fmamk_f32 v170, v65, 0x3dd53b94, v160
	v_fmamk_f32 v171, v66, 0x3dd53b94, v160
	v_fmamk_f32 v232, v67, 0x3dd53b94, v160
	v_fmamk_f32 v233, v68, 0x3dd53b94, v160
	v_fmamk_f32 v162, v69, 0x3dd53b94, v160
	v_fmamk_f32 v163, v70, 0x3dd53b94, v160
	v_fmamk_f32 v166, v73, 0x3dd53b94, v160
	v_fmamk_f32 v167, v74, 0x3dd53b94, v160
	v_fmamk_f32 v168, v75, 0x3dd53b94, v160
	v_fmamk_f32 v161, v76, 0x3dd53b94, v160
	v_exp_f32_e32 v157, v80
	v_exp_f32_e32 v159, v81
	v_exp_f32_e32 v155, v82
	v_exp_f32_e32 v158, v83
	v_exp_f32_e32 v154, v84
	v_exp_f32_e32 v156, v85
	v_exp_f32_e32 v152, v86
	v_exp_f32_e32 v153, v87
	v_exp_f32_e32 v149, v88
	v_exp_f32_e32 v151, v89
	v_exp_f32_e32 v148, v90
	v_exp_f32_e32 v150, v91
	v_exp_f32_e32 v145, v92
	v_exp_f32_e32 v147, v93
	v_exp_f32_e32 v144, v94
	v_exp_f32_e32 v146, v95
	v_fmamk_f32 v234, v77, 0x3dd53b94, v160
	v_fmamk_f32 v235, v78, 0x3dd53b94, v160
	v_fmac_f32_e32 v160, 0x3dd53b94, v79
	s_waitcnt lgkmcnt(0)
	s_barrier
	ds_read_b128 v[64:67], v205 offset:32768
	ds_read_b128 v[68:71], v205 offset:40960
	ds_read_b128 v[192:195], v206 offset:32768
	ds_read_b128 v[236:239], v206 offset:40960
	v_exp_f32_e32 v174, v169
	v_exp_f32_e32 v175, v170
	s_waitcnt lgkmcnt(3)
	v_mfma_f32_32x32x16_bf16 v[80:95], v[64:67], v[136:139], 0
	v_exp_f32_e32 v176, v171
	v_exp_f32_e32 v177, v232
	v_exp_f32_e32 v162, v162
	v_exp_f32_e32 v163, v163
	v_exp_f32_e32 v232, v165
	v_exp_f32_e32 v161, v161
	v_exp_f32_e32 v234, v234
	s_waitcnt lgkmcnt(2)
	v_mfma_f32_32x32x16_bf16 v[64:79], v[68:71], v[136:139], 0
	v_exp_f32_e32 v235, v235
	v_exp_f32_e32 v160, v160
	s_waitcnt lgkmcnt(1)
	v_mfma_f32_32x32x16_bf16 v[80:95], v[192:195], v[132:135], v[80:95]
	s_waitcnt lgkmcnt(0)
	v_mfma_f32_32x32x16_bf16 v[64:79], v[236:239], v[132:135], v[64:79]
	ds_read_b128 v[192:195], v208 offset:32768
	ds_read_b128 v[236:239], v208 offset:40960
	s_waitcnt lgkmcnt(1)
	v_mfma_f32_32x32x16_bf16 v[80:95], v[192:195], v[128:131], v[80:95]
	s_waitcnt lgkmcnt(0)
	v_mfma_f32_32x32x16_bf16 v[64:79], v[236:239], v[128:131], v[64:79]
	ds_read_b128 v[192:195], v209 offset:32768
	ds_read_b128 v[236:239], v209 offset:40960
	s_waitcnt lgkmcnt(1)
	v_mfma_f32_32x32x16_bf16 v[80:95], v[192:195], v[124:127], v[80:95]
	s_waitcnt lgkmcnt(0)
	v_mfma_f32_32x32x16_bf16 v[64:79], v[236:239], v[124:127], v[64:79]
	ds_read_b128 v[192:195], v210 offset:32768
	ds_read_b128 v[236:239], v210 offset:40960
	s_waitcnt lgkmcnt(1)
	v_mfma_f32_32x32x16_bf16 v[80:95], v[192:195], v[120:123], v[80:95]
	s_waitcnt lgkmcnt(0)
	v_mfma_f32_32x32x16_bf16 v[64:79], v[236:239], v[120:123], v[64:79]
	ds_read_b128 v[192:195], v212 offset:32768
	ds_read_b128 v[236:239], v212 offset:40960
	s_waitcnt lgkmcnt(1)
	v_mfma_f32_32x32x16_bf16 v[80:95], v[192:195], v[140:143], v[80:95]
	s_waitcnt lgkmcnt(0)
	v_mfma_f32_32x32x16_bf16 v[64:79], v[236:239], v[140:143], v[64:79]
	ds_read_b128 v[192:195], v211 offset:32768
	ds_read_b128 v[236:239], v211 offset:40960
	s_waitcnt lgkmcnt(1)
; __device__ __forceinline__ void finishSM(f32x16& p0, f32x16& p1, float alpha, float& l_reg, bf16x8& pa0, bf16x8& pa1, bf16x8& pa2, bf16x8& pa3) {
;   for (int r = 0; r < 16; ++r) p1[r] = __builtin_amdgcn_exp2f(p1[r]);
;   float ps = 0; for (int r = 0; r < 16; ++r) ps += p0[r]; for (int r = 0; r < 16; ++r) ps += p1[r];
;   { auto rr = __builtin_amdgcn_permlane32_swap(__float_as_uint(ps), __float_as_uint(ps), false, false);
;     ps = __uint_as_float(rr[0]) + __uint_as_float(rr[1]); }
;   l_reg = l_reg * alpha + ps;
;     ...
;   PK4(p0, 0, pa0); PK4(p0, 8, pa1); PK4(p1, 0, pa2); PK4(p1, 8, pa3);
;     ...
; }
; __device__ __forceinline__ void qkt(f32x16& p0, f32x16& p1, const char* Kn, const char* Kp, const bf16x8* qr, int r32, int hi) {
;   p0 = f32x16{}; p1 = f32x16{};
; #pragma unroll
;   for (int d0 = 0; d0 < 8; ++d0) { int cb = (d0 * 16 + hi * 8) * 2;
;     bf16x8 b0 = *reinterpret_cast<const bf16x8*>(Kn + KSWZ(r32, cb));
;     bf16x8 b1 = *reinterpret_cast<const bf16x8*>(Kn + KSWZ(32 + r32, cb));
;     p0 = __builtin_amdgcn_mfma_f32_32x32x16_bf16(b0, qr[d0], p0, 0, 0, 0);
;     p1 = __builtin_amdgcn_mfma_f32_32x32x16_bf16(b1, qr[d0], p1, 0, 0, 0); }
; #pragma unroll
;   for (int d1 = 0; d1 < 4; ++d1) { int cb = (d1 * 16 + hi * 8) * 2;
;     bf16x8 b0 = *reinterpret_cast<const bf16x8*>(Kp + KPSWZ(r32, cb));
;     bf16x8 b1 = *reinterpret_cast<const bf16x8*>(Kp + KPSWZ(32 + r32, cb));
;     p0 = __builtin_amdgcn_mfma_f32_32x32x16_bf16(b0, qr[8 + d1], p0, 0, 0, 0);
;     p1 = __builtin_amdgcn_mfma_f32_32x32x16_bf16(b1, qr[8 + d1], p1, 0, 0, 0); }
; }
; __device__ __forceinline__ int v_st(int k, int c) { const int kk = (k & ~0xC) | ((k & 4) << 1) | ((k & 8) >> 1); return ((kk >> 3) * 4 + (c >> 5)) * 512 + ((kk & 7) * 32 + (c & 31)) * 2; }
; __device__ __forceinline__ int v_rd_base(int lane) { return ((lane & 3) << 3) | (((lane >> 2) & 3) << 6) | (((lane >> 4) & 1) << 5) | (((lane >> 5) & 1) << 8); }
; template <int OFF> __device__ __forceinline__ s16x4 tr_read(int vb) {
;   s16x4 r; asm volatile("ds_read_b64_tr_b16 %0, %1 offset:%2" : "=&v"(r) : "v"(vb), "i"(OFF) : "memory"); return r;
; }
; template <int D0> __device__ __forceinline__ void pv_one(f32x16& od, int vb, bf16x8 pa0, bf16x8 pa1, bf16x8 pa2, bf16x8 pa3) {
	v_mfma_f32_32x32x16_bf16 v[80:95], v[192:195], v[116:119], v[80:95]
	s_waitcnt lgkmcnt(0)
	v_mfma_f32_32x32x16_bf16 v[64:79], v[236:239], v[116:119], v[64:79]
	ds_read_b128 v[192:195], v207 offset:32768
	ds_read_b128 v[236:239], v207 offset:40960
	s_waitcnt lgkmcnt(1)
	v_mfma_f32_32x32x16_bf16 v[80:95], v[192:195], v[112:115], v[80:95]
	s_waitcnt lgkmcnt(0)
	v_mfma_f32_32x32x16_bf16 v[64:79], v[236:239], v[112:115], v[64:79]
	ds_read_b128 v[192:195], v214
	ds_read_b128 v[236:239], v214 offset:4096
	s_waitcnt lgkmcnt(1)
	v_mfma_f32_32x32x16_bf16 v[80:95], v[192:195], v[108:111], v[80:95]
	s_waitcnt lgkmcnt(0)
	v_mfma_f32_32x32x16_bf16 v[64:79], v[236:239], v[108:111], v[64:79]
	ds_read_b128 v[192:195], v216
	ds_read_b128 v[236:239], v216 offset:4096
	s_waitcnt lgkmcnt(1)
	v_mfma_f32_32x32x16_bf16 v[80:95], v[192:195], v[104:107], v[80:95]
	s_waitcnt lgkmcnt(0)
	v_mfma_f32_32x32x16_bf16 v[64:79], v[236:239], v[104:107], v[64:79]
	ds_read_b128 v[192:195], v218
	ds_read_b128 v[236:239], v218 offset:4096
	s_waitcnt lgkmcnt(1)
	v_mfma_f32_32x32x16_bf16 v[80:95], v[192:195], v[100:103], v[80:95]
	s_waitcnt lgkmcnt(0)
	v_mfma_f32_32x32x16_bf16 v[64:79], v[236:239], v[100:103], v[64:79]
	ds_read_b128 v[192:195], v220
	ds_read_b128 v[236:239], v220 offset:4096
	s_waitcnt lgkmcnt(1)
	v_mfma_f32_32x32x16_bf16 v[80:95], v[192:195], v[96:99], v[80:95]
	v_exp_f32_e32 v195, v164
	v_add_f32_e32 v164, 0, v157
	v_add_f32_e32 v164, v159, v164
	v_add_f32_e32 v164, v155, v164
	v_add_f32_e32 v164, v158, v164
	v_add_f32_e32 v164, v154, v164
	v_add_f32_e32 v164, v156, v164
	v_add_f32_e32 v164, v152, v164
	v_add_f32_e32 v164, v153, v164
	v_add_f32_e32 v164, v149, v164
	v_add_f32_e32 v164, v151, v164
	v_add_f32_e32 v164, v148, v164
	v_add_f32_e32 v164, v150, v164
	v_add_f32_e32 v164, v145, v164
	v_add_f32_e32 v164, v147, v164
	v_add_f32_e32 v164, v144, v164
	v_add_f32_e32 v164, v146, v164
	v_exp_f32_e32 v194, v233
	v_add_f32_e32 v164, v174, v164
	v_add_f32_e32 v164, v175, v164
	v_add_f32_e32 v164, v176, v164
	v_add_f32_e32 v164, v177, v164
	v_add_f32_e32 v164, v194, v164
	v_exp_f32_e32 v233, v166
	v_add_f32_e32 v164, v162, v164
	s_waitcnt lgkmcnt(0)
	v_mfma_f32_32x32x16_bf16 v[64:79], v[236:239], v[96:99], v[64:79]
	v_exp_f32_e32 v236, v167
	v_add_f32_e32 v164, v163, v164
	v_exp_f32_e32 v239, v168
	v_add_f32_e32 v164, v195, v164
	v_add_f32_e32 v164, v232, v164
	v_add_f32_e32 v164, v233, v164
	v_add_f32_e32 v164, v236, v164
	v_add_f32_e32 v164, v239, v164
	v_add_f32_e32 v164, v161, v164
	v_add_f32_e32 v164, v234, v164
	v_add_f32_e32 v164, v235, v164
	v_add_f32_e32 v237, v160, v164
	v_mov_b32_e32 v238, v237
	v_cvt_pk_bf16_f32 v164, v157, v159
	v_cvt_pk_bf16_f32 v165, v155, v158
	v_cvt_pk_bf16_f32 v166, v154, v156
	v_cvt_pk_bf16_f32 v167, v152, v153
	s_nop 1
	v_permlane32_swap_b32_e32 v237, v238
	v_permlane32_swap_b32_e32 v164, v166
	v_permlane32_swap_b32_e32 v165, v167
	v_cvt_pk_bf16_f32 v168, v149, v151
	v_cvt_pk_bf16_f32 v169, v148, v150
	v_cvt_pk_bf16_f32 v170, v145, v147
	v_cvt_pk_bf16_f32 v171, v144, v146
	v_cvt_pk_bf16_f32 v192, v174, v175
	v_cvt_pk_bf16_f32 v193, v176, v177
	v_cvt_pk_bf16_f32 v194, v194, v162
	v_cvt_pk_bf16_f32 v195, v163, v195
	v_cvt_pk_bf16_f32 v232, v232, v233
	v_cvt_pk_bf16_f32 v233, v236, v239
	v_cvt_pk_bf16_f32 v234, v161, v234
	v_cvt_pk_bf16_f32 v235, v235, v160
	s_nop 0
	v_permlane32_swap_b32_e32 v168, v170
	v_permlane32_swap_b32_e32 v169, v171
	v_permlane32_swap_b32_e32 v192, v194
	v_permlane32_swap_b32_e32 v193, v195
	v_permlane32_swap_b32_e32 v232, v234
	v_permlane32_swap_b32_e32 v233, v235
	s_add_i32 s8, s31, 64
	s_cmp_lt_u32 s11, 2
	s_cselect_b32 s8, s8, s34
	v_add_u32_e32 v144, s8, v198
	v_ashrrev_i32_e32 v145, 31, v144
	v_lshlrev_b64 v[144:145], 12, v[144:145]
	v_lshl_add_u64 v[148:149], v[180:181], 0, v[144:145]
	v_add_u32_e32 v144, s8, v200
	v_ashrrev_i32_e32 v145, 31, v144
	v_lshlrev_b64 v[144:145], 12, v[144:145]
	v_lshl_add_u64 v[152:153], v[180:181], 0, v[144:145]
	v_add_u32_e32 v160, s8, v199
	global_load_dwordx4 v[144:147], v[148:149], off offset:256
	s_nop 0
	global_load_dwordx4 v[148:151], v[148:149], off
	s_nop 0
	global_load_dwordx4 v[156:159], v[152:153], off offset:256
	s_nop 0
	global_load_dwordx4 v[152:155], v[152:153], off
	v_ashrrev_i32_e32 v161, 31, v160
	v_lshlrev_b64 v[160:161], 10, v[160:161]
	v_lshl_add_u64 v[160:161], v[182:183], 0, v[160:161]
	global_load_dwordx4 v[160:163], v[160:161], off
	ds_read_b64_tr_b16 v[240:241], v196 offset:0
	ds_read_b64_tr_b16 v[242:243], v196 offset:0x800
	ds_read_b64_tr_b16 v[244:245], v196 offset:0x1000
	ds_read_b64_tr_b16 v[246:247], v196 offset:0x1800
	ds_read_b64_tr_b16 v[248:249], v196 offset:0x2000
	ds_read_b64_tr_b16 v[250:251], v196 offset:0x2800
	ds_read_b64_tr_b16 v[174:175], v196 offset:0x3000
	ds_read_b64_tr_b16 v[176:177], v196 offset:0x3800
	s_waitcnt lgkmcnt(0)
	s_nop 0
	v_mfma_f32_32x32x16_bf16 v[0:15], v[164:167], v[240:243], v[0:15]
	v_mfma_f32_32x32x16_bf16 v[0:15], v[168:171], v[244:247], v[0:15]
	v_mfma_f32_32x32x16_bf16 v[0:15], v[192:195], v[248:251], v[0:15]
	v_mfma_f32_32x32x16_bf16 v[0:15], v[232:235], v[174:177], v[0:15]
	ds_read_b64_tr_b16 v[174:175], v196 offset:0x200
	ds_read_b64_tr_b16 v[176:177], v196 offset:0xa00
	ds_read_b64_tr_b16 v[240:241], v196 offset:0x1200
	ds_read_b64_tr_b16 v[242:243], v196 offset:0x1a00
	ds_read_b64_tr_b16 v[244:245], v196 offset:0x2200
	ds_read_b64_tr_b16 v[246:247], v196 offset:0x2a00
	ds_read_b64_tr_b16 v[248:249], v196 offset:0x3200
	ds_read_b64_tr_b16 v[250:251], v196 offset:0x3a00
	s_waitcnt lgkmcnt(0)
; __device__ __forceinline__ void partialSM(f32x16& p0, f32x16& p1, float& m_reg, float& mn, float& alpha) {
;   constexpr float C = SCALE * 1.4426950408889634f;
;   float pmax = p0[0]; for (int r = 1; r < 16; ++r) pmax = fmaxf(pmax, p0[r]); for (int r = 0; r < 16; ++r) pmax = fmaxf(pmax, p1[r]);
;   { auto rr = __builtin_amdgcn_permlane32_swap(__float_as_uint(pmax), __float_as_uint(pmax), false, false);
;     pmax = fmaxf(__uint_as_float(rr[0]), __uint_as_float(rr[1])); }
;   if (__builtin_expect(__all(pmax - m_reg <= THR / SCALE), 1)) { mn = m_reg; alpha = 1.f; }
;   else { mn = fmaxf(m_reg, pmax); alpha = __builtin_amdgcn_exp2f((m_reg - mn) * C); m_reg = mn; }
;   float mnC = -mn * C;
;   for (int r = 0; r < 16; ++r) p0[r] = fmaf(p0[r], C, mnC); for (int r = 0; r < 16; ++r) p1[r] = fmaf(p1[r], C, mnC);
;   for (int r = 0; r < 16; ++r) p0[r] = __builtin_amdgcn_exp2f(p0[r]);
; }
; __device__ __forceinline__ void finishSM(f32x16& p0, f32x16& p1, float alpha, float& l_reg, bf16x8& pa0, bf16x8& pa1, bf16x8& pa2, bf16x8& pa3) {
;   for (int r = 0; r < 16; ++r) p1[r] = __builtin_amdgcn_exp2f(p1[r]);
;   float ps = 0; for (int r = 0; r < 16; ++r) ps += p0[r]; for (int r = 0; r < 16; ++r) ps += p1[r];
;   { auto rr = __builtin_amdgcn_permlane32_swap(__float_as_uint(ps), __float_as_uint(ps), false, false);
;     ps = __uint_as_float(rr[0]) + __uint_as_float(rr[1]); }
;   l_reg = l_reg * alpha + ps;
;     ...
;   PK4(p0, 0, pa0); PK4(p0, 8, pa1); PK4(p1, 0, pa2); PK4(p1, 8, pa3);
;     ...
; }
; __device__ __forceinline__ void qkt(f32x16& p0, f32x16& p1, const char* Kn, const char* Kp, const bf16x8* qr, int r32, int hi) {
;   p0 = f32x16{}; p1 = f32x16{};
; #pragma unroll
;   for (int d0 = 0; d0 < 8; ++d0) { int cb = (d0 * 16 + hi * 8) * 2;
;     bf16x8 b0 = *reinterpret_cast<const bf16x8*>(Kn + KSWZ(r32, cb));
;     bf16x8 b1 = *reinterpret_cast<const bf16x8*>(Kn + KSWZ(32 + r32, cb));
;     p0 = __builtin_amdgcn_mfma_f32_32x32x16_bf16(b0, qr[d0], p0, 0, 0, 0);
;     p1 = __builtin_amdgcn_mfma_f32_32x32x16_bf16(b1, qr[d0], p1, 0, 0, 0); }
; #pragma unroll
;   for (int d1 = 0; d1 < 4; ++d1) { int cb = (d1 * 16 + hi * 8) * 2;
;     bf16x8 b0 = *reinterpret_cast<const bf16x8*>(Kp + KPSWZ(r32, cb));
;     bf16x8 b1 = *reinterpret_cast<const bf16x8*>(Kp + KPSWZ(32 + r32, cb));
;     p0 = __builtin_amdgcn_mfma_f32_32x32x16_bf16(b0, qr[8 + d1], p0, 0, 0, 0);
	s_nop 0
	v_mfma_f32_32x32x16_bf16 v[48:63], v[164:167], v[174:177], v[48:63]
	ds_read_b64_tr_b16 v[174:175], v196 offset:0x400
	ds_read_b64_tr_b16 v[176:177], v196 offset:0xc00
	v_mfma_f32_32x32x16_bf16 v[48:63], v[168:171], v[240:243], v[48:63]
	ds_read_b64_tr_b16 v[240:241], v196 offset:0x1400
	ds_read_b64_tr_b16 v[242:243], v196 offset:0x1c00
	v_mfma_f32_32x32x16_bf16 v[48:63], v[192:195], v[244:247], v[48:63]
	ds_read_b64_tr_b16 v[244:245], v196 offset:0x2400
	ds_read_b64_tr_b16 v[246:247], v196 offset:0x2c00
	v_mfma_f32_32x32x16_bf16 v[48:63], v[232:235], v[248:251], v[48:63]
	ds_read_b64_tr_b16 v[248:249], v196 offset:0x3400
	ds_read_b64_tr_b16 v[250:251], v196 offset:0x3c00
	s_waitcnt lgkmcnt(0)
	v_mfma_f32_32x32x16_bf16 v[32:47], v[164:167], v[174:177], v[32:47]
	ds_read_b64_tr_b16 v[174:175], v196 offset:0x600
	ds_read_b64_tr_b16 v[176:177], v196 offset:0xe00
	v_mfma_f32_32x32x16_bf16 v[32:47], v[168:171], v[240:243], v[32:47]
	ds_read_b64_tr_b16 v[240:241], v196 offset:0x1600
	ds_read_b64_tr_b16 v[242:243], v196 offset:0x1e00
	v_mfma_f32_32x32x16_bf16 v[32:47], v[192:195], v[244:247], v[32:47]
	ds_read_b64_tr_b16 v[244:245], v196 offset:0x2600
	ds_read_b64_tr_b16 v[246:247], v196 offset:0x2e00
	v_mfma_f32_32x32x16_bf16 v[32:47], v[232:235], v[248:251], v[32:47]
	ds_read_b64_tr_b16 v[248:249], v196 offset:0x3600
	ds_read_b64_tr_b16 v[250:251], v196 offset:0x3e00
	s_waitcnt lgkmcnt(0)
	v_mfma_f32_32x32x16_bf16 v[16:31], v[164:167], v[174:177], v[16:31]
	v_max_f32_e32 v164, v81, v81
	v_max_f32_e32 v165, v80, v80
	v_max_f32_e32 v164, v165, v164
	v_max3_f32 v164, v164, v82, v83
	v_max3_f32 v164, v164, v84, v85
	v_max3_f32 v164, v164, v86, v87
	v_max3_f32 v164, v164, v88, v89
	v_max3_f32 v164, v164, v90, v91
	v_max3_f32 v164, v164, v92, v93
	v_mfma_f32_32x32x16_bf16 v[16:31], v[168:171], v[240:243], v[16:31]
	v_max3_f32 v164, v164, v94, v95
	v_max3_f32 v164, v164, v64, v65
	v_max3_f32 v164, v164, v66, v67
	v_max3_f32 v164, v164, v68, v69
	v_max3_f32 v164, v164, v70, v71
	v_max3_f32 v164, v164, v72, v73
	v_max3_f32 v164, v164, v74, v75
	v_max3_f32 v164, v164, v76, v77
	v_mfma_f32_32x32x16_bf16 v[16:31], v[192:195], v[244:247], v[16:31]
	v_max3_f32 v164, v164, v78, v79
	v_mov_b32_e32 v165, v164
	s_nop 1
	v_permlane32_swap_b32_e32 v164, v165
	v_max_f32_e32 v165, v165, v165
	v_max_f32_e32 v164, v164, v164
	v_max_f32_e32 v164, v164, v165
	v_sub_f32_e32 v165, v164, v224
	v_cmp_ge_f32_e32 vcc, s33, v165
	v_max_f32_e32 v165, v224, v224
	v_max_f32_e32 v165, v165, v164
	v_mfma_f32_32x32x16_bf16 v[16:31], v[232:235], v[248:251], v[16:31]
	v_sub_f32_e32 v164, v224, v165
	v_mul_f32_e32 v164, 0x3dd53b94, v164
	v_exp_f32_e32 v164, v164
	s_cmp_eq_u64 vcc, exec
	s_cselect_b64 s[8:9], -1, 0
	s_waitcnt vmcnt(0)
	ds_write_b128 v203, v[148:151] offset:49152
	ds_write_b128 v204, v[152:155] offset:49152
	ds_write_b128 v223, v[160:163]
	s_barrier
	s_waitcnt vmcnt(0)
	v_cndmask_b32_e64 v164, v164, 1.0, s[8:9]
	v_cmp_gt_f32_e32 vcc, 1.0, v164
	ds_write_b128 v201, v[144:147] offset:16384
	ds_write_b128 v202, v[156:159] offset:16384
	s_cbranch_vccz .LBB0_1461
	s_and_saveexec_b64 s[24:25], s[6:7]
	ds_write_b32 v186, v164 offset:128
	s_or_b64 exec, exec, s[24:25]
	s_waitcnt lgkmcnt(0)
	v_add_u32_e32 v156, v179, v172
	ds_read_b128 v[144:147], v156 offset:224
	ds_read_b128 v[148:151], v156 offset:192
	ds_read_b128 v[152:155], v156 offset:160
	ds_read_b128 v[156:159], v156 offset:128
	s_waitcnt lgkmcnt(3)
	v_pk_mul_f32 v[12:13], v[12:13], v[144:145]
	s_waitcnt lgkmcnt(2)
	v_pk_mul_f32 v[8:9], v[8:9], v[148:149]
	s_waitcnt lgkmcnt(1)
	v_pk_mul_f32 v[4:5], v[4:5], v[152:153]
	v_pk_mul_f32 v[14:15], v[14:15], v[146:147]
	v_pk_mul_f32 v[10:11], v[10:11], v[150:151]
	v_pk_mul_f32 v[6:7], v[6:7], v[154:155]
	s_waitcnt lgkmcnt(0)
	v_pk_mul_f32 v[2:3], v[2:3], v[158:159]
	v_pk_mul_f32 v[0:1], v[0:1], v[156:157]
	v_pk_mul_f32 v[60:61], v[60:61], v[144:145]
	v_pk_mul_f32 v[56:57], v[56:57], v[148:149]
	v_pk_mul_f32 v[52:53], v[52:53], v[152:153]
	v_pk_mul_f32 v[62:63], v[62:63], v[146:147]
	v_pk_mul_f32 v[58:59], v[58:59], v[150:151]
	v_pk_mul_f32 v[54:55], v[54:55], v[154:155]
	v_pk_mul_f32 v[50:51], v[50:51], v[158:159]
	v_pk_mul_f32 v[48:49], v[48:49], v[156:157]
	v_pk_mul_f32 v[44:45], v[44:45], v[144:145]
	v_pk_mul_f32 v[40:41], v[40:41], v[148:149]
	v_pk_mul_f32 v[36:37], v[36:37], v[152:153]
	v_pk_mul_f32 v[46:47], v[46:47], v[146:147]
	v_pk_mul_f32 v[42:43], v[42:43], v[150:151]
	v_pk_mul_f32 v[38:39], v[38:39], v[154:155]
	v_pk_mul_f32 v[34:35], v[34:35], v[158:159]
	v_pk_mul_f32 v[32:33], v[32:33], v[156:157]
	v_pk_mul_f32 v[28:29], v[28:29], v[144:145]
	v_pk_mul_f32 v[24:25], v[24:25], v[148:149]
	v_pk_mul_f32 v[20:21], v[20:21], v[152:153]
	v_pk_mul_f32 v[30:31], v[30:31], v[146:147]
	v_pk_mul_f32 v[26:27], v[26:27], v[150:151]
	v_pk_mul_f32 v[22:23], v[22:23], v[154:155]
	v_pk_mul_f32 v[18:19], v[18:19], v[158:159]
	v_pk_mul_f32 v[16:17], v[16:17], v[156:157]
